# attnA: first K fragment batch reads spread one per MFMA gap with counted waits
# speedup vs baseline: 1.0130x; 1.0130x over previous
; #define FA_SB() __builtin_amdgcn_sched_barrier(0)
; #define FA_PVM(G) do { o[(G) & 3] = __builtin_amdgcn_mfma_f32_32x32x16_bf16(__builtin_bit_cast(bf16x8, vr[(G) % 3]), __builtin_bit_cast(bf16x8, PWC[(G) >> 2]), o[(G) & 3], 0, 0, 0); if ((G) + 3 < 16) vr[(G) % 3] = FA_VFRAG((G) + 3); } while (0)
; #define FA_EXP2(J, PX, R) do { const float e0_ = __builtin_amdgcn_exp2f(PX[R]), e1_ = __builtin_amdgcn_exp2f(PX[(R) + 1]); ps += e0_; ps += e1_; PWN[(J) >> 2][(J) & 3] = cvtpk(e0_, e1_); } while (0)
; __device__ __forceinline__ void attn_unit_a(FLAS unsigned char* lds, const Unit u) {
;     ...
;         for (int g = 8; g < 16; ++g) { FA_PVM(g); FA_EXP2(g - 8, pC0, 2 * (g - 8));
;             if (g == 12) { kf[0] = FA_KF(0, 0); kf[1] = FA_KF(0, 1); kf[2] = FA_KF(1, 0); kf[3] = FA_KF(1, 1); }
;             FA_SB(); }
;         float cbN; bool ziN; const int inx = (i + 1 < NT) ? i + 1 : NT - 1;
;         FA_BIAS(inx, pN0, pN1, cbN, ziN);
.LBB0_442:
	s_waitcnt lgkmcnt(2)
	v_mfma_f32_32x32x16_bf16 v[48:63], v[136:139], v[192:195], v[48:63]
	ds_read_b128 v[136:139], v200 offset:30272
	v_exp_f32_e32 v96, v96
	v_exp_f32_e32 v97, v97
	s_waitcnt lgkmcnt(2)
	v_mfma_f32_32x32x16_bf16 v[32:47], v[128:131], v[192:195], v[32:47]
	ds_read_b128 v[128:131], v200 offset:16480
	v_exp_f32_e32 v98, v98
	v_exp_f32_e32 v99, v99
	v_add_f32_e32 v212, v96, v212
	v_add_f32_e32 v212, v97, v212
	s_waitcnt lgkmcnt(2)
	v_mfma_f32_32x32x16_bf16 v[16:31], v[132:135], v[192:195], v[16:31]
	ds_read_b128 v[132:135], v200 offset:21088
	v_exp_f32_e32 v100, v100
	v_exp_f32_e32 v101, v101
	v_add_f32_e32 v212, v98, v212
	v_add_f32_e32 v212, v99, v212
	s_waitcnt lgkmcnt(2)
	v_mfma_f32_32x32x16_bf16 v[0:15], v[136:139], v[192:195], v[0:15]
	ds_read_b128 v[136:139], v200 offset:25696
	v_exp_f32_e32 v102, v102
	v_exp_f32_e32 v103, v103
	v_add_f32_e32 v212, v100, v212
	v_add_f32_e32 v212, v101, v212
	s_waitcnt lgkmcnt(2)
	v_mfma_f32_32x32x16_bf16 v[48:63], v[128:131], v[188:191], v[48:63]
	ds_read_b128 v[128:131], v200 offset:30304
	ds_read_b128 v[204:207], v247 offset:8192
	v_exp_f32_e32 v104, v104
	v_exp_f32_e32 v105, v105
	v_add_f32_e32 v212, v102, v212
	v_add_f32_e32 v212, v103, v212
	s_waitcnt lgkmcnt(3)
	v_mfma_f32_32x32x16_bf16 v[32:47], v[132:135], v[188:191], v[32:47]
	ds_read_b128 v[200:203], v247 offset:8704
	v_exp_f32_e32 v106, v106
	v_exp_f32_e32 v107, v107
	v_add_f32_e32 v212, v104, v212
	v_add_f32_e32 v212, v105, v212
	s_waitcnt lgkmcnt(3)
	v_mfma_f32_32x32x16_bf16 v[16:31], v[136:139], v[188:191], v[16:31]
	ds_read_b128 v[196:199], v248 offset:8192
	v_exp_f32_e32 v108, v108
	v_exp_f32_e32 v109, v109
	v_add_f32_e32 v212, v106, v212
	v_add_f32_e32 v212, v107, v212
	s_waitcnt lgkmcnt(3)
	v_mfma_f32_32x32x16_bf16 v[0:15], v[128:131], v[188:191], v[0:15]
	ds_read_b128 v[192:195], v248 offset:8704
	v_exp_f32_e32 v110, v110
	v_exp_f32_e32 v111, v111
	v_add_f32_e32 v212, v108, v212
	v_add_f32_e32 v212, v109, v212
	s_sub_i32 s12, s48, 31
	s_cmpk_lt_i32 s12, 0x22f
	s_cbranch_scc0 .Lz_plus_e
	s_cmpk_gt_i32 s48, 0xfd92
	s_cbranch_scc1 .Lgather_e
	v_sub_f32_e32 v142, s100, v211
	s_branch .Lz_chk_e

; #define FA_SB() __builtin_amdgcn_sched_barrier(0)
; #define FA_EXP2(J, PX, R) do { const float e0_ = __builtin_amdgcn_exp2f(PX[R]), e1_ = __builtin_amdgcn_exp2f(PX[(R) + 1]); ps += e0_; ps += e1_; PWN[(J) >> 2][(J) & 3] = cvtpk(e0_, e1_); } while (0)
; __device__ __forceinline__ void attn_unit_a(FLAS unsigned char* lds, const Unit u) {
;     ...
;         if (ziN) { pN0 = __builtin_amdgcn_mfma_f32_32x32x16_bf16(kf[0], qr[0], z16, 0, 0, 0); FA_EXP2(8, pC1, 0); FA_SB(); pN1 = __builtin_amdgcn_mfma_f32_32x32x16_bf16(kf[1], qr[0], z16, 0, 0, 0); }
;         else { pN0 = __builtin_amdgcn_mfma_f32_32x32x16_bf16(kf[0], qr[0], pN0, 0, 0, 0); FA_EXP2(8, pC1, 0); FA_SB(); pN1 = __builtin_amdgcn_mfma_f32_32x32x16_bf16(kf[1], qr[0], pN1, 0, 0, 0); }
.Lz_go_e:
	s_waitcnt lgkmcnt(3)
	v_mfma_f32_32x32x16_bf16 v[64:79], v[204:207], v[160:163], v[144:159]
	v_exp_f32_e32 v112, v112
	v_exp_f32_e32 v113, v113
	v_add_f32_e32 v212, v110, v212
	v_add_f32_e32 v212, v111, v212
	s_waitcnt lgkmcnt(2)
	v_mfma_f32_32x32x16_bf16 v[80:95], v[200:203], v[160:163], v[144:159]
	v_exp_f32_e32 v114, v114
	v_exp_f32_e32 v115, v115
	s_branch .Lk2_e

; #define FA_SB() __builtin_amdgcn_sched_barrier(0)
; #define FA_EXP2(J, PX, R) do { const float e0_ = __builtin_amdgcn_exp2f(PX[R]), e1_ = __builtin_amdgcn_exp2f(PX[(R) + 1]); ps += e0_; ps += e1_; PWN[(J) >> 2][(J) & 3] = cvtpk(e0_, e1_); } while (0)
; __device__ __forceinline__ void attn_unit_a(FLAS unsigned char* lds, const Unit u) {
;     ...
;         else { pN0 = __builtin_amdgcn_mfma_f32_32x32x16_bf16(kf[0], qr[0], pN0, 0, 0, 0); FA_EXP2(8, pC1, 0); FA_SB(); pN1 = __builtin_amdgcn_mfma_f32_32x32x16_bf16(kf[1], qr[0], pN1, 0, 0, 0); }
;         kf[0] = FA_KF(2, 0); kf[1] = FA_KF(2, 1); FA_EXP2(9, pC1, 2); FA_SB();
;         pN0 = __builtin_amdgcn_mfma_f32_32x32x16_bf16(kf[2], qr[1], pN0, 0, 0, 0); FA_EXP2(10, pC1, 4); FA_SB();
;         pN1 = __builtin_amdgcn_mfma_f32_32x32x16_bf16(kf[3], qr[1], pN1, 0, 0, 0); kf[2] = FA_KF(3, 0); kf[3] = FA_KF(3, 1); FA_EXP2(11, pC1, 6); FA_SB();
;         pN0 = __builtin_amdgcn_mfma_f32_32x32x16_bf16(kf[0], qr[2], pN0, 0, 0, 0); FA_EXP2(12, pC1, 8); FA_SB();
;         pN1 = __builtin_amdgcn_mfma_f32_32x32x16_bf16(kf[1], qr[2], pN1, 0, 0, 0); FA_EXP2(13, pC1, 10); FA_SB();
;         pN0 = __builtin_amdgcn_mfma_f32_32x32x16_bf16(kf[2], qr[3], pN0, 0, 0, 0); FA_EXP2(14, pC1, 12); FA_SB();
;         pN1 = __builtin_amdgcn_mfma_f32_32x32x16_bf16(kf[3], qr[3], pN1, 0, 0, 0); FA_EXP2(15, pC1, 14); FA_SB();
.Lk2_e:
	ds_read_b128 v[128:131], v249 offset:8192
	ds_read_b128 v[132:135], v249 offset:8704
	s_add_i32 s34, s19, 2
	s_waitcnt lgkmcnt(3)
	v_mfma_f32_32x32x16_bf16 v[64:79], v[196:199], v[164:167], v[64:79]
	v_exp_f32_e32 v116, v116
	v_exp_f32_e32 v117, v117
	s_waitcnt lgkmcnt(2)
	v_mfma_f32_32x32x16_bf16 v[80:95], v[192:195], v[164:167], v[80:95]
	ds_read_b128 v[136:139], v250 offset:8192
	ds_read_b128 v[140:143], v250 offset:8704
	v_exp_f32_e32 v118, v118
	v_exp_f32_e32 v119, v119
	s_waitcnt lgkmcnt(3)
	v_mfma_f32_32x32x16_bf16 v[64:79], v[128:131], v[168:171], v[64:79]
	v_exp_f32_e32 v120, v120
	v_exp_f32_e32 v121, v121
	s_waitcnt lgkmcnt(2)
	v_mfma_f32_32x32x16_bf16 v[80:95], v[132:135], v[168:171], v[80:95]
	v_exp_f32_e32 v122, v122
	v_exp_f32_e32 v123, v123
	s_waitcnt lgkmcnt(1)
	v_mfma_f32_32x32x16_bf16 v[64:79], v[136:139], v[172:175], v[64:79]
	v_exp_f32_e32 v124, v124
	v_exp_f32_e32 v125, v125
	s_waitcnt lgkmcnt(0)
	v_mfma_f32_32x32x16_bf16 v[80:95], v[140:143], v[172:175], v[80:95]
	v_exp_f32_e32 v126, v126
	v_exp_f32_e32 v127, v127
	s_andn2_b64 vcc, exec, s[0:1]
	s_cbranch_vccnz .LBB0_456
	s_and_b32 s0, s34, 2
	s_mulk_i32 s0, 0x4800
	v_add_u32_e32 v128, s0, v245
	v_add_u32_e32 v129, 0x4000, v128
	v_add_u32_e32 v128, 0x6000, v128
	s_waitcnt vmcnt(2)
	ds_write_b128 v225, v[176:179]
	s_waitcnt vmcnt(1)
	ds_write2_b64 v129, v[180:181], v[182:183] offset1:2
	s_waitcnt vmcnt(0)
	ds_write2_b64 v128, v[184:185], v[186:187] offset0:128 offset1:130

; #define FA_SB() __builtin_amdgcn_sched_barrier(0)
; #define FA_PVM(G) do { o[(G) & 3] = __builtin_amdgcn_mfma_f32_32x32x16_bf16(__builtin_bit_cast(bf16x8, vr[(G) % 3]), __builtin_bit_cast(bf16x8, PWC[(G) >> 2]), o[(G) & 3], 0, 0, 0); if ((G) + 3 < 16) vr[(G) % 3] = FA_VFRAG((G) + 3); } while (0)
; #define FA_EXP2(J, PX, R) do { const float e0_ = __builtin_amdgcn_exp2f(PX[R]), e1_ = __builtin_amdgcn_exp2f(PX[(R) + 1]); ps += e0_; ps += e1_; PWN[(J) >> 2][(J) & 3] = cvtpk(e0_, e1_); } while (0)
; __device__ __forceinline__ void attn_unit_a(FLAS unsigned char* lds, const Unit u) {
;     ...
;         for (int g = 8; g < 16; ++g) { FA_PVM(g); FA_EXP2(g - 8, pC0, 2 * (g - 8));
;             if (g == 12) { kf[0] = FA_KF(0, 0); kf[1] = FA_KF(0, 1); kf[2] = FA_KF(1, 0); kf[3] = FA_KF(1, 1); }
;             FA_SB(); }
;         float cbN; bool ziN; const int inx = (i + 1 < NT) ? i + 1 : NT - 1;
;         FA_BIAS(inx, pN0, pN1, cbN, ziN);
.LBB0_462:
	s_waitcnt lgkmcnt(2)
	v_mfma_f32_32x32x16_bf16 v[48:63], v[136:139], v[140:143], v[48:63]
	ds_read_b128 v[136:139], v201 offset:30272
	v_exp_f32_e32 v64, v64
	v_exp_f32_e32 v65, v65
	v_cvt_pk_bf16_f32 v232, v120, v121
	v_cvt_pk_bf16_f32 v233, v122, v123
	s_waitcnt lgkmcnt(2)
	v_mfma_f32_32x32x16_bf16 v[32:47], v[128:131], v[140:143], v[32:47]
	ds_read_b128 v[128:131], v201 offset:16480
	v_exp_f32_e32 v66, v66
	v_exp_f32_e32 v67, v67
	v_add_f32_e32 v212, v64, v212
	v_add_f32_e32 v212, v65, v212
	v_cvt_pk_bf16_f32 v234, v124, v125
	v_cvt_pk_bf16_f32 v235, v126, v127
	s_waitcnt lgkmcnt(2)
	v_mfma_f32_32x32x16_bf16 v[16:31], v[132:135], v[140:143], v[16:31]
	ds_read_b128 v[132:135], v201 offset:21088
	v_exp_f32_e32 v68, v68
	v_exp_f32_e32 v69, v69
	v_add_f32_e32 v212, v66, v212
	v_add_f32_e32 v212, v67, v212
	s_waitcnt lgkmcnt(2)
	v_mfma_f32_32x32x16_bf16 v[0:15], v[136:139], v[140:143], v[0:15]
	ds_read_b128 v[136:139], v201 offset:25696
	v_exp_f32_e32 v70, v70
	v_exp_f32_e32 v71, v71
	v_add_f32_e32 v212, v68, v212
	v_add_f32_e32 v212, v69, v212
	s_waitcnt lgkmcnt(2)
	v_mfma_f32_32x32x16_bf16 v[48:63], v[128:131], v[232:235], v[48:63]
	ds_read_b128 v[128:131], v201 offset:30304
	ds_read_b128 v[200:203], v247
	v_exp_f32_e32 v72, v72
	v_exp_f32_e32 v73, v73
	v_add_f32_e32 v212, v70, v212
	v_add_f32_e32 v212, v71, v212
	s_waitcnt lgkmcnt(3)
	v_mfma_f32_32x32x16_bf16 v[32:47], v[132:135], v[232:235], v[32:47]
	ds_read_b128 v[196:199], v247 offset:512
	v_exp_f32_e32 v74, v74
	v_exp_f32_e32 v75, v75
	v_add_f32_e32 v212, v72, v212
	v_add_f32_e32 v212, v73, v212
	s_waitcnt lgkmcnt(3)
	v_mfma_f32_32x32x16_bf16 v[16:31], v[136:139], v[232:235], v[16:31]
	ds_read_b128 v[192:195], v248
	v_exp_f32_e32 v76, v76
	v_exp_f32_e32 v77, v77
	v_add_f32_e32 v212, v74, v212
	v_add_f32_e32 v212, v75, v212
	s_waitcnt lgkmcnt(3)
	v_mfma_f32_32x32x16_bf16 v[0:15], v[128:131], v[232:235], v[0:15]
	ds_read_b128 v[188:191], v248 offset:512
	v_exp_f32_e32 v78, v78
	v_exp_f32_e32 v79, v79
	v_add_f32_e32 v212, v76, v212
	v_add_f32_e32 v212, v77, v212
	s_min_u32 s12, s34, 0x7f
	s_lshl_b32 s12, s12, 6
	s_sub_i32 s14, s12, s47
	s_sub_i32 s15, s14, 31
	s_cmpk_lt_i32 s15, 0x22f
	s_cbranch_scc0 .Lz_plus_o
	s_cmpk_gt_i32 s14, 0xfd92
	s_cbranch_scc1 .Lgather_o
	v_sub_f32_e32 v126, s100, v211
	s_branch .Lz_chk_o

; #define FA_SB() __builtin_amdgcn_sched_barrier(0)
; #define FA_EXP2(J, PX, R) do { const float e0_ = __builtin_amdgcn_exp2f(PX[R]), e1_ = __builtin_amdgcn_exp2f(PX[(R) + 1]); ps += e0_; ps += e1_; PWN[(J) >> 2][(J) & 3] = cvtpk(e0_, e1_); } while (0)
; __device__ __forceinline__ void attn_unit_a(FLAS unsigned char* lds, const Unit u) {
;     ...
;         if (ziN) { pN0 = __builtin_amdgcn_mfma_f32_32x32x16_bf16(kf[0], qr[0], z16, 0, 0, 0); FA_EXP2(8, pC1, 0); FA_SB(); pN1 = __builtin_amdgcn_mfma_f32_32x32x16_bf16(kf[1], qr[0], z16, 0, 0, 0); }
;         else { pN0 = __builtin_amdgcn_mfma_f32_32x32x16_bf16(kf[0], qr[0], pN0, 0, 0, 0); FA_EXP2(8, pC1, 0); FA_SB(); pN1 = __builtin_amdgcn_mfma_f32_32x32x16_bf16(kf[1], qr[0], pN1, 0, 0, 0); }
.Lz_go_o:
	s_waitcnt lgkmcnt(3)
	v_mfma_f32_32x32x16_bf16 v[96:111], v[200:203], v[160:163], v[144:159]
	v_exp_f32_e32 v80, v80
	v_exp_f32_e32 v81, v81
	v_add_f32_e32 v212, v78, v212
	v_add_f32_e32 v212, v79, v212
	s_waitcnt lgkmcnt(2)
	v_mfma_f32_32x32x16_bf16 v[112:127], v[196:199], v[160:163], v[144:159]
	v_exp_f32_e32 v82, v82
	v_exp_f32_e32 v83, v83
	s_branch .Lk2_o

; #define FA_SB() __builtin_amdgcn_sched_barrier(0)
; #define FA_EXP2(J, PX, R) do { const float e0_ = __builtin_amdgcn_exp2f(PX[R]), e1_ = __builtin_amdgcn_exp2f(PX[(R) + 1]); ps += e0_; ps += e1_; PWN[(J) >> 2][(J) & 3] = cvtpk(e0_, e1_); } while (0)
; __device__ __forceinline__ void attn_unit_a(FLAS unsigned char* lds, const Unit u) {
;     ...
;         else { pN0 = __builtin_amdgcn_mfma_f32_32x32x16_bf16(kf[0], qr[0], pN0, 0, 0, 0); FA_EXP2(8, pC1, 0); FA_SB(); pN1 = __builtin_amdgcn_mfma_f32_32x32x16_bf16(kf[1], qr[0], pN1, 0, 0, 0); }
;         kf[0] = FA_KF(2, 0); kf[1] = FA_KF(2, 1); FA_EXP2(9, pC1, 2); FA_SB();
;         pN0 = __builtin_amdgcn_mfma_f32_32x32x16_bf16(kf[2], qr[1], pN0, 0, 0, 0); FA_EXP2(10, pC1, 4); FA_SB();
;         pN1 = __builtin_amdgcn_mfma_f32_32x32x16_bf16(kf[3], qr[1], pN1, 0, 0, 0); kf[2] = FA_KF(3, 0); kf[3] = FA_KF(3, 1); FA_EXP2(11, pC1, 6); FA_SB();
;         pN0 = __builtin_amdgcn_mfma_f32_32x32x16_bf16(kf[0], qr[2], pN0, 0, 0, 0); FA_EXP2(12, pC1, 8); FA_SB();
;         pN1 = __builtin_amdgcn_mfma_f32_32x32x16_bf16(kf[1], qr[2], pN1, 0, 0, 0); FA_EXP2(13, pC1, 10); FA_SB();
;         pN0 = __builtin_amdgcn_mfma_f32_32x32x16_bf16(kf[2], qr[3], pN0, 0, 0, 0); FA_EXP2(14, pC1, 12); FA_SB();
;         pN1 = __builtin_amdgcn_mfma_f32_32x32x16_bf16(kf[3], qr[3], pN1, 0, 0, 0); FA_EXP2(15, pC1, 14); FA_SB();
.Lk2_o:
	ds_read_b128 v[128:131], v249
	ds_read_b128 v[132:135], v249 offset:512
	s_waitcnt lgkmcnt(3)
	v_mfma_f32_32x32x16_bf16 v[96:111], v[192:195], v[164:167], v[96:111]
	v_exp_f32_e32 v84, v84
	v_exp_f32_e32 v85, v85
	s_waitcnt lgkmcnt(2)
	v_mfma_f32_32x32x16_bf16 v[112:127], v[188:191], v[164:167], v[112:127]
	ds_read_b128 v[136:139], v250
	ds_read_b128 v[140:143], v250 offset:512
	v_exp_f32_e32 v86, v86
	v_exp_f32_e32 v87, v87
	s_waitcnt lgkmcnt(3)
	v_mfma_f32_32x32x16_bf16 v[96:111], v[128:131], v[168:171], v[96:111]
	v_exp_f32_e32 v88, v88
	v_exp_f32_e32 v89, v89
	s_waitcnt lgkmcnt(2)
	v_mfma_f32_32x32x16_bf16 v[112:127], v[132:135], v[168:171], v[112:127]
	v_exp_f32_e32 v90, v90
	v_exp_f32_e32 v91, v91
	s_waitcnt lgkmcnt(1)
	v_mfma_f32_32x32x16_bf16 v[96:111], v[136:139], v[172:175], v[96:111]
	v_exp_f32_e32 v92, v92
	v_exp_f32_e32 v93, v93
	s_waitcnt lgkmcnt(0)
	v_mfma_f32_32x32x16_bf16 v[112:127], v[140:143], v[172:175], v[112:127]
	v_exp_f32_e32 v94, v94
	v_exp_f32_e32 v95, v95
	s_andn2_b64 vcc, exec, s[20:21]
	s_cbranch_vccnz .LBB0_476
	v_add_u32_e32 v128, s18, v245
	v_add_u32_e32 v129, 0x4000, v128
	v_add_u32_e32 v128, 0x6000, v128
	s_waitcnt vmcnt(2)
	ds_write_b128 v225, v[176:179] offset:8192
	s_waitcnt vmcnt(1)
	ds_write2_b64 v129, v[180:181], v[182:183] offset1:2
	s_waitcnt vmcnt(0)
	ds_write2_b64 v128, v[184:185], v[186:187] offset0:128 offset1:130
